# B2 loop: next pair K/V LDS staging issued before the second tile PV MFMAs instead of after them
# speedup vs baseline: 1.0266x; 1.0065x over previous
; template <bool INIT = true> __device__ __forceinline__ void qk_lds(f32x16& p0, f32x16& p1, const LAS unsigned char* buf, const bf16x8 (&qr)[4], int r32, int hi) {
;     const LAS unsigned char* kp = buf + pi_row(r32) * TP + hi * 16;
;     if (INIT) { p0 = (f32x16){}; p1 = (f32x16){}; }
;     bf16x8 kf[8];
; #pragma unroll
;     for (int d0 = 0; d0 < 4; ++d0) { kf[2 * d0] = *(const LAS bf16x8*)(kp + d0 * 32); kf[2 * d0 + 1] = *(const LAS bf16x8*)(kp + 32 * TP + d0 * 32); }
;     __builtin_amdgcn_s_setprio(1);
; #pragma unroll
;     for (int d0 = 0; d0 < 4; ++d0) { p0 = MFMA32(kf[2 * d0], qr[d0], p0); p1 = MFMA32(kf[2 * d0 + 1], qr[d0], p1); }
;     __builtin_amdgcn_s_setprio(0);
; }
; __device__ __forceinline__ void pv_lds(f32x16& o0, f32x16& o1, const LAS unsigned char* buf, const f32x16& p0, const f32x16& p1, int r32, int hi) {
;     const LAS unsigned char* vp = buf + TILE_B + r32 * TP + hi * 16;
;     bf16x8 pf[4], vf[8];
; #pragma unroll
;     for (int half = 0; half < 2; ++half)
; #pragma unroll
;         for (int s = 0; s < 2; ++s) {
;             const f32x16& p = half ? p1 : p0;
;             u32x4 w; w.x = cvtpk(p[8 * s + 0], p[8 * s + 1]); w.y = cvtpk(p[8 * s + 2], p[8 * s + 3]); w.z = cvtpk(p[8 * s + 4], p[8 * s + 5]); w.w = cvtpk(p[8 * s + 6], p[8 * s + 7]);
;             pf[half * 2 + s] = __builtin_bit_cast(bf16x8, w);
;             vf[(half * 2 + s) * 2] = *(const LAS bf16x8*)(vp + half * 64 + s * 32); vf[(half * 2 + s) * 2 + 1] = *(const LAS bf16x8*)(vp + 32 * TP + half * 64 + s * 32);
;         }
;     __builtin_amdgcn_s_setprio(1);
; #pragma unroll
;     for (int k = 0; k < 4; ++k) { o0 = MFMA32(vf[2 * k], pf[k], o0); o1 = MFMA32(vf[2 * k + 1], pf[k], o1); }
;     __builtin_amdgcn_s_setprio(0);
; }
; template <bool FIXED> __device__ __forceinline__ void attnB_blk(const bf16* Q, const bf16* K, const bf16* Vt, bf16* O, const unsigned long long* MASK, float ref, LAS unsigned char* lds, int vcu, int G, int tid) {
;     ...
;             for (int k = 0; k < 2; ++k) {
;                 if (it + k < ntile) {
;                     LAS unsigned char* buf = pb + k * KVBUF_B;
;                     f32x16 p0, p1; b_mask_init(p0, p1, k ? mb : ma, hi, FIXED ? ref : 0.f);
;                     qk_lds<false>(p0, p1, buf, qr, r32, hi);
;                     if (FIXED) l += exp_tile(p0, p1); else softmax_step(p0, p1, m, l, o0, o1);
.LBB0_785:
	v_lshrrev_b32_e32 v0, v134, v4
	v_bfe_i32 v17, v0, 23, 1
	v_bfe_i32 v18, v0, 22, 1
	v_lshrrev_b32_e32 v2, v134, v5
	v_bfi_b32 v79, v17, v16, v240
	v_bfe_i32 v19, v0, 21, 1
	v_bfi_b32 v78, v18, v16, v240
	v_bfe_i32 v20, v0, 20, 1
	v_bfi_b32 v77, v19, v16, v240
	v_bfe_i32 v21, v0, 19, 1
	v_bfi_b32 v76, v20, v16, v240
	v_bfe_i32 v22, v0, 18, 1
	v_bfi_b32 v75, v21, v16, v240
	v_bfe_i32 v23, v0, 17, 1
	v_bfi_b32 v74, v22, v16, v240
	v_bfe_i32 v24, v0, 16, 1
	v_bfi_b32 v73, v23, v16, v240
	v_bfe_i32 v17, v0, 7, 1
	v_bfi_b32 v72, v24, v16, v240
	v_bfe_i32 v18, v0, 6, 1
	v_bfi_b32 v71, v17, v16, v240
	v_bfe_i32 v19, v0, 5, 1
	v_bfi_b32 v70, v18, v16, v240
	v_bfe_i32 v20, v0, 4, 1
	v_bfi_b32 v69, v19, v16, v240
	v_bfe_i32 v21, v0, 3, 1
	v_bfi_b32 v68, v20, v16, v240
	v_bfe_i32 v22, v0, 2, 1
	v_bfi_b32 v67, v21, v16, v240
	v_bfe_i32 v23, v0, 1, 1
	v_bfe_i32 v24, v0, 0, 1
	v_bfi_b32 v66, v22, v16, v240
	v_bfi_b32 v65, v23, v16, v240
	v_bfe_i32 v17, v2, 23, 1
	v_bfi_b32 v64, v24, v16, v240
	v_bfe_i32 v18, v2, 22, 1
	v_bfi_b32 v95, v17, v16, v240
	v_bfe_i32 v19, v2, 21, 1
	v_bfi_b32 v94, v18, v16, v240
	v_bfe_i32 v20, v2, 20, 1
	v_bfi_b32 v93, v19, v16, v240
	v_bfe_i32 v21, v2, 19, 1
	v_bfi_b32 v92, v20, v16, v240
	v_bfe_i32 v22, v2, 18, 1
	v_bfi_b32 v91, v21, v16, v240
	v_bfe_i32 v23, v2, 17, 1
	v_bfi_b32 v90, v22, v16, v240
	v_bfe_i32 v24, v2, 16, 1
	v_bfi_b32 v89, v23, v16, v240
	v_bfe_i32 v17, v2, 7, 1
	v_bfi_b32 v88, v24, v16, v240
	v_bfe_i32 v18, v2, 6, 1
	v_bfi_b32 v87, v17, v16, v240
	v_bfe_i32 v19, v2, 5, 1
	v_bfi_b32 v86, v18, v16, v240
	v_bfe_i32 v20, v2, 4, 1
	v_bfi_b32 v85, v19, v16, v240
	v_bfe_i32 v21, v2, 3, 1
	v_bfi_b32 v84, v20, v16, v240
	v_bfe_i32 v22, v2, 2, 1
	v_bfi_b32 v83, v21, v16, v240
	v_bfe_i32 v23, v2, 1, 1
	v_bfi_b32 v82, v22, v16, v240
	v_bfe_i32 v24, v2, 0, 1
	ds_read_b128 v[2:5], v7 offset:23040
	ds_read_b128 v[8:11], v7 offset:18432
	ds_read_b128 v[12:15], v7 offset:18464
	ds_read_b128 v[160:163], v7 offset:23072
	ds_read_b128 v[164:167], v7 offset:18496
	ds_read_b128 v[168:171], v7 offset:23104
	ds_read_b128 v[172:175], v7 offset:18528
	ds_read_b128 v[176:179], v7 offset:23136
	v_bfi_b32 v81, v23, v16, v240
	v_bfi_b32 v80, v24, v16, v240
	s_setprio 1
	s_waitcnt lgkmcnt(6)
	v_mfma_f32_32x32x16_bf16 v[64:79], v[8:11], v[96:99], v[64:79]
	v_mfma_f32_32x32x16_bf16 v[80:95], v[2:5], v[96:99], v[80:95]
	s_waitcnt lgkmcnt(5)
	v_mfma_f32_32x32x16_bf16 v[64:79], v[12:15], v[100:103], v[64:79]
	s_waitcnt lgkmcnt(4)
	v_mfma_f32_32x32x16_bf16 v[80:95], v[160:163], v[100:103], v[80:95]
	s_waitcnt lgkmcnt(3)
	v_mfma_f32_32x32x16_bf16 v[64:79], v[164:167], v[108:111], v[64:79]
	s_waitcnt lgkmcnt(2)
	v_mfma_f32_32x32x16_bf16 v[80:95], v[168:171], v[108:111], v[80:95]
	s_waitcnt lgkmcnt(1)
	v_mfma_f32_32x32x16_bf16 v[64:79], v[172:175], v[112:115], v[64:79]
	s_waitcnt lgkmcnt(0)
	v_mfma_f32_32x32x16_bf16 v[80:95], v[176:179], v[112:115], v[80:95]
	s_setprio 0
	s_nop 8
	v_exp_f32_e32 v7, v64
	s_nop 0
	v_exp_f32_e32 v147, v80
	v_exp_f32_e32 v2, v65
	v_exp_f32_e32 v0, v81
	v_exp_f32_e32 v159, v82
	v_add_f32_e32 v3, v7, v147
	v_exp_f32_e32 v88, v88
	v_pk_add_f32 v[4:5], v[2:3], v[0:1]
	v_exp_f32_e32 v3, v66
	v_pk_add_f32 v[80:81], v[4:5], v[4:5] op_sel_hi:[0,1]
	v_exp_f32_e32 v4, v67
	v_exp_f32_e32 v80, v83
	v_add_f32_e32 v5, v3, v159
	v_cvt_pk_bf16_f32 v2, v7, v2
	v_cvt_pk_bf16_f32 v3, v3, v4
	v_pk_add_f32 v[8:9], v[4:5], v[80:81]
	v_exp_f32_e32 v5, v68
	v_pk_add_f32 v[82:83], v[8:9], v[8:9] op_sel_hi:[0,1]
	v_exp_f32_e32 v81, v84
	v_exp_f32_e32 v8, v69
	v_exp_f32_e32 v82, v85
	v_add_f32_e32 v9, v5, v81
	v_cvt_pk_bf16_f32 v4, v5, v8
	v_pk_add_f32 v[10:11], v[8:9], v[82:83]
	v_exp_f32_e32 v9, v70
	v_pk_add_f32 v[84:85], v[10:11], v[10:11] op_sel_hi:[0,1]
	v_exp_f32_e32 v83, v86
	v_exp_f32_e32 v10, v71
	v_exp_f32_e32 v84, v87
	v_exp_f32_e32 v70, v72
	v_add_f32_e32 v11, v9, v83
	v_cvt_pk_bf16_f32 v5, v9, v10
	v_pk_add_f32 v[12:13], v[10:11], v[84:85]
	s_nop 0
	v_pk_add_f32 v[160:161], v[12:13], v[12:13] op_sel_hi:[0,1]
	v_exp_f32_e32 v12, v73
	v_exp_f32_e32 v160, v89
	v_add_f32_e32 v13, v70, v88
	v_exp_f32_e32 v89, v90
	v_pk_add_f32 v[14:15], v[12:13], v[160:161]
	s_nop 0
	v_pk_add_f32 v[162:163], v[14:15], v[14:15] op_sel_hi:[0,1]
	v_exp_f32_e32 v13, v74
	v_exp_f32_e32 v14, v75
	v_exp_f32_e32 v162, v91
	v_exp_f32_e32 v161, v92
	v_add_f32_e32 v15, v13, v89
	v_cvt_pk_bf16_f32 v12, v70, v12
	v_pk_add_f32 v[64:65], v[14:15], v[162:163]
	v_exp_f32_e32 v15, v76
	v_pk_add_f32 v[90:91], v[64:65], v[64:65] op_sel_hi:[0,1]
	v_exp_f32_e32 v64, v77
	v_exp_f32_e32 v90, v93
	v_add_f32_e32 v65, v15, v161
	v_cvt_pk_bf16_f32 v13, v13, v14
	v_cvt_pk_bf16_f32 v14, v15, v64
	v_pk_add_f32 v[66:67], v[64:65], v[90:91]
	v_exp_f32_e32 v65, v78
	v_pk_add_f32 v[92:93], v[66:67], v[66:67] op_sel_hi:[0,1]
	v_exp_f32_e32 v91, v94
	v_exp_f32_e32 v66, v79
	v_exp_f32_e32 v92, v95
	v_cvt_pk_bf16_f32 v77, v159, v80
	v_add_f32_e32 v67, v65, v91
	v_cvt_pk_bf16_f32 v15, v65, v66
	v_pk_add_f32 v[68:69], v[66:67], v[92:93]
	v_cvt_pk_bf16_f32 v78, v81, v82
	v_add_f32_e32 v11, v68, v69
	v_add_f32_e32 v145, v145, v11
	ds_read_b128 v[8:11], v6 offset:32256
	ds_read_b128 v[64:67], v6 offset:27648
	ds_read_b128 v[68:71], v6 offset:27680
	ds_read_b128 v[72:75], v6 offset:32288
	v_cvt_pk_bf16_f32 v79, v83, v84
	ds_read_b128 v[80:83], v6 offset:27712
	ds_read_b128 v[84:87], v6 offset:32320
	v_cvt_pk_bf16_f32 v88, v88, v160
	v_cvt_pk_bf16_f32 v89, v89, v162
	v_cvt_pk_bf16_f32 v90, v161, v90
	v_cvt_pk_bf16_f32 v91, v91, v92
	ds_read_b128 v[92:95], v6 offset:27744
	ds_read_b128 v[160:163], v6 offset:32352
	v_cvt_pk_bf16_f32 v76, v147, v0
	s_andn2_b64 vcc, exec, s[10:11]
	s_cbranch_vccnz .Lb2_pv_nowrite
	s_andn2_b32 s22, 1, s18
	s_mul_i32 s22, s22, 0x9000
	v_add_u32_e32 v0, s22, v133
	s_waitcnt vmcnt(3)
	ds_write_b128 v0, v[104:107]
	s_waitcnt vmcnt(2)
	ds_write_b128 v0, v[120:123] offset:9216
	s_waitcnt vmcnt(1)
	ds_write_b128 v0, v[124:127] offset:18432
	s_waitcnt vmcnt(0)
	ds_write_b128 v0, v[128:131] offset:27648
	s_setprio 1
	s_waitcnt lgkmcnt(10)
	v_mfma_f32_32x32x16_bf16 v[48:63], v[64:67], v[2:5], v[48:63]
	v_mfma_f32_32x32x16_bf16 v[32:47], v[8:11], v[2:5], v[32:47]
	s_waitcnt lgkmcnt(9)
	v_mfma_f32_32x32x16_bf16 v[48:63], v[68:71], v[12:15], v[48:63]
	s_waitcnt lgkmcnt(8)
	v_mfma_f32_32x32x16_bf16 v[32:47], v[72:75], v[12:15], v[32:47]
	s_waitcnt lgkmcnt(7)
	v_mfma_f32_32x32x16_bf16 v[48:63], v[80:83], v[76:79], v[48:63]
	s_waitcnt lgkmcnt(6)
	v_mfma_f32_32x32x16_bf16 v[32:47], v[84:87], v[76:79], v[32:47]
	s_waitcnt lgkmcnt(5)
	v_mfma_f32_32x32x16_bf16 v[48:63], v[92:95], v[88:91], v[48:63]
	s_waitcnt lgkmcnt(4)
	v_mfma_f32_32x32x16_bf16 v[32:47], v[160:163], v[88:91], v[32:47]
	s_setprio 0
	s_branch .LBB0_782
; #define LAS __attribute__((address_space(3)))
; #define MFMA32(a, b, c) __builtin_amdgcn_mfma_f32_32x32x16_bf16((a), (b), (c), 0, 0, 0)
; #define WG_BARRIER_L() do { asm volatile("s_waitcnt lgkmcnt(0)" ::: "memory"); __builtin_amdgcn_s_barrier(); asm volatile("" ::: "memory"); } while (0)
; __device__ __forceinline__ void pv_lds(f32x16& o0, f32x16& o1, const LAS unsigned char* buf, const f32x16& p0, const f32x16& p1, int r32, int hi) {
;     ...
;     __builtin_amdgcn_s_setprio(1);
; #pragma unroll
;     for (int k = 0; k < 4; ++k) { o0 = MFMA32(vf[2 * k], pf[k], o0); o1 = MFMA32(vf[2 * k + 1], pf[k], o1); }
;     __builtin_amdgcn_s_setprio(0);
; template <bool FIXED> __device__ __forceinline__ void attnB_blk(const bf16* Q, const bf16* K, const bf16* Vt, bf16* O, const unsigned long long* MASK, float ref, LAS unsigned char* lds, int vcu, int G, int tid) {
;     ...
;             if (it + 2 < ntl) { LAS unsigned char* nb = lds + (((it >> 1) + 1) & 1) * PAIR_B; kv_write(sa, nb, tid); kv_write(sb, nb + KVBUF_B, tid);
;     ...
;                 kv_issue(sa, Kh, Vth, kbase + (size_t)(it + 2) * 64, tid); kv_issue(sb, Kh, Vth, kbase + (size_t)(it + 3) * 64, tid); kv_write(sa, nb, tid); kv_write(sb, nb + KVBUF_B, tid);
;     ...
;             }
;             WG_BARRIER_L();
.Lb2_pv_nowrite:
	s_setprio 1
	s_waitcnt lgkmcnt(6)
	v_mfma_f32_32x32x16_bf16 v[48:63], v[64:67], v[2:5], v[48:63]
	v_mfma_f32_32x32x16_bf16 v[32:47], v[8:11], v[2:5], v[32:47]
	s_waitcnt lgkmcnt(5)
	v_mfma_f32_32x32x16_bf16 v[48:63], v[68:71], v[12:15], v[48:63]
	s_waitcnt lgkmcnt(4)
	v_mfma_f32_32x32x16_bf16 v[32:47], v[72:75], v[12:15], v[32:47]
	s_waitcnt lgkmcnt(3)
	v_mfma_f32_32x32x16_bf16 v[48:63], v[80:83], v[76:79], v[48:63]
	s_waitcnt lgkmcnt(2)
	v_mfma_f32_32x32x16_bf16 v[32:47], v[84:87], v[76:79], v[32:47]
	s_waitcnt lgkmcnt(1)
	v_mfma_f32_32x32x16_bf16 v[48:63], v[92:95], v[88:91], v[48:63]
	s_waitcnt lgkmcnt(0)
	v_mfma_f32_32x32x16_bf16 v[32:47], v[160:163], v[88:91], v[32:47]
	s_setprio 0
	s_branch .LBB0_782
